# mixer-A main loop: QK^T MFMA snake order (same-accumulator pairs share an operand) on top of v119
# speedup vs baseline: 1.0003x; 1.0003x over previous
.LBB0_276:
	s_mov_b32 s4, s92
	s_mov_b32 s6, s89
	v_cvt_pk_bf16_f32 v154, v90, v91
	v_lshl_add_u32 v210, s7, 1, v235
	ds_read_b64_tr_b16 v[68:69], v210 offset:24576
	ds_read_b64_tr_b16 v[70:71], v210 offset:25088
	v_add_f32_e32 v67, v98, v99
	v_add_f32_e32 v67, v100, v67
	v_add_f32_e32 v67, v101, v67
	v_add_f32_e32 v67, v102, v67
	v_add_f32_e32 v67, v103, v67
	v_cvt_pk_bf16_f32 v174, v98, v99
	v_cvt_pk_bf16_f32 v175, v100, v101
	s_waitcnt lgkmcnt(9)
	v_mfma_f32_32x32x16_bf16 v[130:145], v[206:209], v[166:169], 0
	ds_read_b64_tr_b16 v[72:73], v210 offset:28672
	ds_read_b64_tr_b16 v[74:75], v210 offset:29184
	v_add_f32_e32 v67, v104, v67
	v_add_f32_e32 v67, v105, v67
	v_add_f32_e32 v67, v106, v67
	v_add_f32_e32 v67, v107, v67
	v_cvt_pk_bf16_f32 v176, v102, v103
	v_cvt_pk_bf16_f32 v177, v104, v105
	s_waitcnt lgkmcnt(10)
	v_mfma_f32_32x32x16_bf16 v[114:129], v[198:201], v[166:169], 0
	ds_read_b64_tr_b16 v[76:77], v210 offset:25600
	ds_read_b64_tr_b16 v[78:79], v210 offset:26112
	v_add_f32_e32 v67, v108, v67
	v_add_f32_e32 v67, v109, v67
	v_add_f32_e32 v67, v110, v67
	v_add_f32_e32 v67, v111, v67
	v_cvt_pk_bf16_f32 v170, v106, v107
	v_cvt_pk_bf16_f32 v171, v108, v109
	s_waitcnt lgkmcnt(11)
	v_mfma_f32_32x32x16_bf16 v[114:129], v[194:197], v[158:161], v[114:129]
	ds_read_b64_tr_b16 v[98:99], v210 offset:29696
	ds_read_b64_tr_b16 v[100:101], v210 offset:30208
	v_add_f32_e32 v67, v112, v67
	v_add_f32_e32 v67, v113, v67
	v_add_f32_e32 v67, v82, v67
	v_add_f32_e32 v67, v83, v67
	v_cvt_pk_bf16_f32 v172, v110, v111
	v_cvt_pk_bf16_f32 v173, v112, v113
	s_waitcnt lgkmcnt(12)
	v_mfma_f32_32x32x16_bf16 v[130:145], v[202:205], v[158:161], v[130:145]
	ds_read_b64_tr_b16 v[102:103], v210 offset:26624
	ds_read_b64_tr_b16 v[104:105], v210 offset:27136
	v_add_f32_e32 v67, v84, v67
	v_add_f32_e32 v67, v85, v67
	v_add_f32_e32 v67, v86, v67
	v_add_f32_e32 v67, v87, v67
	v_cvt_pk_bf16_f32 v162, v82, v83
	v_cvt_pk_bf16_f32 v163, v84, v85
	s_waitcnt lgkmcnt(13)
	v_mfma_f32_32x32x16_bf16 v[130:145], v[190:193], v[150:153], v[130:145]
	ds_read_b64_tr_b16 v[106:107], v210 offset:30720
	ds_read_b64_tr_b16 v[108:109], v210 offset:31232
	v_add_f32_e32 v67, v88, v67
	v_add_f32_e32 v67, v89, v67
	v_add_f32_e32 v67, v90, v67
	v_add_f32_e32 v67, v91, v67
	v_cvt_pk_bf16_f32 v164, v86, v87
	v_cvt_pk_bf16_f32 v165, v88, v89
	s_waitcnt lgkmcnt(14)
	v_mfma_f32_32x32x16_bf16 v[114:129], v[186:189], v[150:153], v[114:129]
	ds_read_b64_tr_b16 v[110:111], v210 offset:27648
	ds_read_b64_tr_b16 v[112:113], v210 offset:28160
	v_add_f32_e32 v67, v92, v67
	v_add_f32_e32 v67, v93, v67
	v_add_f32_e32 v67, v94, v67
	v_add_f32_e32 v67, v95, v67
	s_waitcnt lgkmcnt(14)
	v_mfma_f32_32x32x16_bf16 v[114:129], v[178:181], v[146:149], v[114:129]
	ds_read_b64_tr_b16 v[188:189], v210 offset:31744
	ds_read_b64_tr_b16 v[190:191], v210 offset:32256
	v_add_f32_e32 v67, v96, v67
	v_add_f32_e32 v67, v97, v67
	v_add_f32_e32 v67, 0, v67
	v_mfma_f32_32x32x16_bf16 v[130:145], v[182:185], v[146:149], v[130:145]
	s_add_u32 s8, s2, 0xfffe0000
	s_addc_u32 s9, s3, -1
	s_add_i32 s7, s89, s86
	s_mov_b32 s10, m0
	s_mov_b32 m0, s7
	s_nop 0
	global_load_lds_dwordx4 v222, s[8:9]
	s_mov_b32 m0, s10
	s_add_u32 s8, s0, 0xfffe0000
	s_addc_u32 s9, s1, -1
	s_lshl_b32 s7, s92, 1
	s_add_i32 s7, s7, s87
	s_mov_b32 s10, m0
	s_mov_b32 m0, s7
	s_nop 0
	global_load_lds_dwordx4 v223, s[8:9]
	s_mov_b32 m0, s10
	s_add_u32 s8, s0, 0xfffe0080
	s_addc_u32 s9, s1, -1
	s_addk_i32 s7, 0x2000
	s_mov_b32 s10, m0
	s_mov_b32 m0, s7
	s_nop 0
	global_load_lds_dwordx4 v223, s[8:9]
	s_mov_b32 m0, s10
	v_add_f32_e32 v186, v66, v67
	s_waitcnt lgkmcnt(14)
	v_mfma_f32_32x32x16_bf16 v[2:17], v[174:177], v[68:71], v[2:17]
	v_exp_f32_e32 v130, v130
	ds_read_b64_tr_b16 v[192:193], v210 offset:32768
	ds_read_b64_tr_b16 v[194:195], v210 offset:33280
	s_waitcnt lgkmcnt(14)
	v_mfma_f32_32x32x16_bf16 v[18:33], v[174:177], v[72:75], v[18:33]
	v_exp_f32_e32 v131, v131
	v_cvt_pk_bf16_f32 v155, v92, v93
	ds_read_b64_tr_b16 v[90:91], v210 offset:36864
	ds_read_b64_tr_b16 v[92:93], v210 offset:37376
	v_add_u32_e32 v66, s4, v237
	ds_read_b128 v[86:89], v66
	ds_read_b128 v[82:85], v66 offset:512
	s_waitcnt lgkmcnt(14)
	v_mfma_f32_32x32x16_bf16 v[2:17], v[170:173], v[76:79], v[2:17]
	v_exp_f32_e32 v132, v132
	v_cvt_pk_bf16_f32 v156, v94, v95
	ds_read_b64_tr_b16 v[196:197], v210 offset:33792
	ds_read_b64_tr_b16 v[198:199], v210 offset:34304
	ds_read_b128 v[182:185], v66 offset:2048
	ds_read_b128 v[78:81], v66 offset:2560
	v_mfma_f32_32x32x16_bf16 v[18:33], v[170:173], v[98:101], v[18:33]
	v_exp_f32_e32 v133, v133
	v_cvt_pk_bf16_f32 v157, v96, v97
	ds_read_b64_tr_b16 v[94:95], v210 offset:37888
	ds_read_b64_tr_b16 v[96:97], v210 offset:38400
	ds_read_b128 v[178:181], v66 offset:4096
	ds_read_b128 v[74:77], v66 offset:4608
	s_waitcnt lgkmcnt(14)
	v_mfma_f32_32x32x16_bf16 v[2:17], v[162:165], v[102:105], v[2:17]
	v_exp_f32_e32 v134, v134
	ds_read_b64_tr_b16 v[98:99], v210 offset:34816
	ds_read_b64_tr_b16 v[100:101], v210 offset:35328
	ds_read_b128 v[70:73], v66 offset:6144
	ds_read_b128 v[66:69], v66 offset:6656
	v_mfma_f32_32x32x16_bf16 v[18:33], v[162:165], v[106:109], v[18:33]
	v_exp_f32_e32 v135, v135
	ds_read_b64_tr_b16 v[102:103], v210 offset:38912
	ds_read_b64_tr_b16 v[104:105], v210 offset:39424
	v_mfma_f32_32x32x16_bf16 v[2:17], v[154:157], v[110:113], v[2:17]
	v_exp_f32_e32 v136, v136
	ds_read_b64_tr_b16 v[106:107], v210 offset:35840
	ds_read_b64_tr_b16 v[108:109], v210 offset:36352
	v_mfma_f32_32x32x16_bf16 v[18:33], v[154:157], v[188:191], v[18:33]
	v_exp_f32_e32 v137, v137
	ds_read_b64_tr_b16 v[110:111], v210 offset:39936
	ds_read_b64_tr_b16 v[112:113], v210 offset:40448
	s_waitcnt lgkmcnt(14)
	v_mfma_f32_32x32x16_bf16 v[34:49], v[174:177], v[192:195], v[34:49]
	v_exp_f32_e32 v138, v138
	v_exp_f32_e32 v114, v114
	v_exp_f32_e32 v115, v115
	v_mfma_f32_32x32x16_bf16 v[50:65], v[174:177], v[90:93], v[50:65]
	v_exp_f32_e32 v139, v139
	v_exp_f32_e32 v116, v116
	v_exp_f32_e32 v117, v117
	v_mfma_f32_32x32x16_bf16 v[34:49], v[170:173], v[196:199], v[34:49]
	v_exp_f32_e32 v140, v140
	v_exp_f32_e32 v118, v118
	v_exp_f32_e32 v119, v119
	s_waitcnt lgkmcnt(12)
	v_mfma_f32_32x32x16_bf16 v[50:65], v[170:173], v[94:97], v[50:65]
	v_exp_f32_e32 v141, v141
	v_exp_f32_e32 v120, v120
	v_exp_f32_e32 v121, v121
	s_waitcnt lgkmcnt(8)
	v_mfma_f32_32x32x16_bf16 v[34:49], v[162:165], v[98:101], v[34:49]
	v_exp_f32_e32 v142, v142
	v_exp_f32_e32 v122, v122
	v_exp_f32_e32 v123, v123
	s_waitcnt lgkmcnt(4)
	v_mfma_f32_32x32x16_bf16 v[50:65], v[162:165], v[102:105], v[50:65]
	v_exp_f32_e32 v143, v143
	v_exp_f32_e32 v124, v124
	v_exp_f32_e32 v125, v125
	s_waitcnt lgkmcnt(2)
	v_mfma_f32_32x32x16_bf16 v[34:49], v[154:157], v[106:109], v[34:49]
	v_exp_f32_e32 v144, v144
	v_exp_f32_e32 v126, v126
	v_exp_f32_e32 v127, v127
	s_waitcnt lgkmcnt(0)
	v_mfma_f32_32x32x16_bf16 v[50:65], v[154:157], v[110:113], v[50:65]
	v_exp_f32_e32 v145, v145
	v_exp_f32_e32 v128, v128
	v_exp_f32_e32 v129, v129
	s_waitcnt vmcnt(3) lgkmcnt(0)
	s_barrier
	s_add_i32 s7, s92, 0x2000
	s_cmpk_lg_i32 s92, 0x4000
	s_cselect_b32 s89, s7, 0
	v_lshl_add_u32 v210, s6, 1, v235
	ds_read_b64_tr_b16 v[188:189], v210 offset:24576
	ds_read_b64_tr_b16 v[190:191], v210 offset:25088
	v_mfma_f32_32x32x16_bf16 v[98:113], v[86:89], v[166:169], 0
	v_add_f32_e32 v90, v130, v131
	v_add_f32_e32 v90, v132, v90
	v_add_f32_e32 v90, v133, v90
	v_add_f32_e32 v90, v134, v90
	v_add_f32_e32 v90, v135, v90
	v_cvt_pk_bf16_f32 v174, v130, v131
	v_cvt_pk_bf16_f32 v175, v132, v133
	ds_read_b64_tr_b16 v[130:131], v210 offset:28672
	ds_read_b64_tr_b16 v[132:133], v210 offset:29184
	v_add_f32_e32 v86, v136, v90
	v_add_f32_e32 v86, v137, v86
	v_add_f32_e32 v86, v138, v86
	v_add_f32_e32 v154, v139, v86
	v_mfma_f32_32x32x16_bf16 v[82:97], v[82:85], v[166:169], 0
	v_cvt_pk_bf16_f32 v176, v134, v135
	v_cvt_pk_bf16_f32 v177, v136, v137
	ds_read_b64_tr_b16 v[134:135], v210 offset:25600
	ds_read_b64_tr_b16 v[136:137], v210 offset:26112
	v_mfma_f32_32x32x16_bf16 v[82:97], v[78:81], v[158:161], v[82:97]
	v_add_f32_e32 v154, v140, v154
	v_add_f32_e32 v154, v141, v154
	v_add_f32_e32 v154, v142, v154
	v_add_f32_e32 v154, v143, v154
	v_cvt_pk_bf16_f32 v170, v138, v139
	v_cvt_pk_bf16_f32 v171, v140, v141
	ds_read_b64_tr_b16 v[138:139], v210 offset:29696
	ds_read_b64_tr_b16 v[140:141], v210 offset:30208
	v_mfma_f32_32x32x16_bf16 v[98:113], v[182:185], v[158:161], v[98:113]
	v_add_f32_e32 v78, v144, v154
	v_add_f32_e32 v78, v145, v78
	v_add_f32_e32 v78, v114, v78
	v_add_f32_e32 v154, v115, v78
	v_cvt_pk_bf16_f32 v172, v142, v143
	v_cvt_pk_bf16_f32 v173, v144, v145
	ds_read_b64_tr_b16 v[78:79], v210 offset:26624
	ds_read_b64_tr_b16 v[80:81], v210 offset:27136
	v_mfma_f32_32x32x16_bf16 v[98:113], v[178:181], v[150:153], v[98:113]
	v_add_f32_e32 v142, v116, v154
	v_add_f32_e32 v142, v117, v142
	v_add_f32_e32 v142, v118, v142
	v_add_f32_e32 v142, v119, v142
	v_cvt_pk_bf16_f32 v162, v114, v115
	v_cvt_pk_bf16_f32 v163, v116, v117
	ds_read_b64_tr_b16 v[114:115], v210 offset:30720
	ds_read_b64_tr_b16 v[116:117], v210 offset:31232
	v_mfma_f32_32x32x16_bf16 v[82:97], v[74:77], v[150:153], v[82:97]
	v_add_f32_e32 v74, v120, v142
	v_add_f32_e32 v74, v121, v74
	v_add_f32_e32 v74, v122, v74
	v_add_f32_e32 v142, v123, v74
	v_cvt_pk_bf16_f32 v164, v118, v119
	v_cvt_pk_bf16_f32 v165, v120, v121
	ds_read_b64_tr_b16 v[74:75], v210 offset:27648
	ds_read_b64_tr_b16 v[76:77], v210 offset:28160
	v_mfma_f32_32x32x16_bf16 v[82:97], v[66:69], v[146:149], v[82:97]
	v_add_f32_e32 v66, v124, v142
	v_add_f32_e32 v66, v125, v66
	v_add_f32_e32 v66, v126, v66
	v_add_f32_e32 v118, v127, v66
	v_mfma_f32_32x32x16_bf16 v[98:113], v[70:73], v[146:149], v[98:113]
	ds_read_b64_tr_b16 v[70:71], v210 offset:31744
	ds_read_b64_tr_b16 v[72:73], v210 offset:32256
	v_add_f32_e32 v66, v128, v118
	v_add_f32_e32 v66, v129, v66
	v_add_f32_e32 v66, 0, v66
	s_add_i32 s6, s92, s86
	s_mov_b32 s7, m0
	s_mov_b32 m0, s6
	s_nop 0
	global_load_lds_dwordx4 v222, s[2:3]
	s_mov_b32 m0, s7
	s_lshl_b32 s6, s89, 1
	s_add_i32 s76, s76, 2
	s_add_i32 s8, s6, s87
	s_mov_b32 s6, m0
	s_mov_b32 m0, s8
	s_nop 0
	global_load_lds_dwordx4 v223, s[0:1]
	s_mov_b32 m0, s6
	s_add_u32 s6, s0, 0x80
	s_addc_u32 s7, s1, 0
	s_addk_i32 s8, 0x2000
	s_mov_b32 s9, m0
	s_mov_b32 m0, s8
	s_nop 0
	global_load_lds_dwordx4 v223, s[6:7]
	s_mov_b32 m0, s9
	v_add_f32_e32 v66, v186, v66
	s_waitcnt lgkmcnt(14)
	v_mfma_f32_32x32x16_bf16 v[2:17], v[174:177], v[188:191], v[2:17]
	v_exp_f32_e32 v98, v98
	v_cvt_pk_bf16_f32 v154, v122, v123
	ds_read_b64_tr_b16 v[118:119], v210 offset:32768
	ds_read_b64_tr_b16 v[120:121], v210 offset:33280
	s_waitcnt lgkmcnt(14)
	v_mfma_f32_32x32x16_bf16 v[18:33], v[174:177], v[130:133], v[18:33]
	v_exp_f32_e32 v99, v99
	v_cvt_pk_bf16_f32 v155, v124, v125
	ds_read_b64_tr_b16 v[122:123], v210 offset:36864
	ds_read_b64_tr_b16 v[124:125], v210 offset:37376
	v_add_u32_e32 v67, s89, v237
	ds_read_b128 v[206:209], v67
	ds_read_b128 v[198:201], v67 offset:512
	s_waitcnt lgkmcnt(14)
	v_mfma_f32_32x32x16_bf16 v[2:17], v[170:173], v[134:137], v[2:17]
	v_exp_f32_e32 v100, v100
	v_cvt_pk_bf16_f32 v156, v126, v127
	ds_read_b64_tr_b16 v[130:131], v210 offset:33792
	ds_read_b64_tr_b16 v[132:133], v210 offset:34304
	ds_read_b128 v[202:205], v67 offset:2048
	ds_read_b128 v[194:197], v67 offset:2560
	v_mfma_f32_32x32x16_bf16 v[18:33], v[170:173], v[138:141], v[18:33]
	v_exp_f32_e32 v101, v101
	v_cvt_pk_bf16_f32 v157, v128, v129
	ds_read_b64_tr_b16 v[126:127], v210 offset:37888
	ds_read_b64_tr_b16 v[128:129], v210 offset:38400
	ds_read_b128 v[190:193], v67 offset:4096
	ds_read_b128 v[186:189], v67 offset:4608
	s_waitcnt lgkmcnt(14)
	v_mfma_f32_32x32x16_bf16 v[2:17], v[162:165], v[78:81], v[2:17]
	v_exp_f32_e32 v102, v102
	ds_read_b64_tr_b16 v[78:79], v210 offset:34816
	ds_read_b64_tr_b16 v[80:81], v210 offset:35328
	ds_read_b128 v[182:185], v67 offset:6144
	ds_read_b128 v[178:181], v67 offset:6656
	v_mfma_f32_32x32x16_bf16 v[18:33], v[162:165], v[114:117], v[18:33]
	v_exp_f32_e32 v103, v103
	ds_read_b64_tr_b16 v[114:115], v210 offset:38912
	ds_read_b64_tr_b16 v[116:117], v210 offset:39424
	v_mfma_f32_32x32x16_bf16 v[2:17], v[154:157], v[74:77], v[2:17]
	v_exp_f32_e32 v104, v104
	ds_read_b64_tr_b16 v[74:75], v210 offset:35840
	ds_read_b64_tr_b16 v[76:77], v210 offset:36352
	v_mfma_f32_32x32x16_bf16 v[18:33], v[154:157], v[70:73], v[18:33]
	v_exp_f32_e32 v105, v105
	ds_read_b64_tr_b16 v[68:69], v210 offset:39936
	ds_read_b64_tr_b16 v[70:71], v210 offset:40448
	s_waitcnt lgkmcnt(14)
	v_mfma_f32_32x32x16_bf16 v[34:49], v[174:177], v[118:121], v[34:49]
	v_exp_f32_e32 v106, v106
	v_exp_f32_e32 v82, v82
	v_exp_f32_e32 v83, v83
	v_mfma_f32_32x32x16_bf16 v[50:65], v[174:177], v[122:125], v[50:65]
	v_exp_f32_e32 v107, v107
	v_exp_f32_e32 v84, v84
	v_exp_f32_e32 v85, v85
	v_mfma_f32_32x32x16_bf16 v[34:49], v[170:173], v[130:133], v[34:49]
	v_exp_f32_e32 v108, v108
	v_exp_f32_e32 v86, v86
	v_exp_f32_e32 v87, v87
	s_waitcnt lgkmcnt(12)
	v_mfma_f32_32x32x16_bf16 v[50:65], v[170:173], v[126:129], v[50:65]
	v_exp_f32_e32 v109, v109
	v_exp_f32_e32 v88, v88
	v_exp_f32_e32 v89, v89
	s_waitcnt lgkmcnt(8)
	v_mfma_f32_32x32x16_bf16 v[34:49], v[162:165], v[78:81], v[34:49]
	v_exp_f32_e32 v110, v110
	v_exp_f32_e32 v90, v90
	v_exp_f32_e32 v91, v91
	s_waitcnt lgkmcnt(4)
	v_mfma_f32_32x32x16_bf16 v[50:65], v[162:165], v[114:117], v[50:65]
	v_exp_f32_e32 v111, v111
	v_exp_f32_e32 v92, v92
	v_exp_f32_e32 v93, v93
	s_waitcnt lgkmcnt(2)
	v_mfma_f32_32x32x16_bf16 v[34:49], v[154:157], v[74:77], v[34:49]
	v_exp_f32_e32 v112, v112
	v_exp_f32_e32 v94, v94
	v_exp_f32_e32 v95, v95
	s_waitcnt lgkmcnt(0)
	v_mfma_f32_32x32x16_bf16 v[50:65], v[154:157], v[68:71], v[50:65]
	v_exp_f32_e32 v113, v113
	v_exp_f32_e32 v96, v96
	v_exp_f32_e32 v97, v97
	s_add_i32 s6, s89, 0x2000
	s_cmpk_lg_i32 s89, 0x4000
	s_cselect_b32 s92, s6, 0
	s_add_u32 s0, s0, 0x40000
	s_addc_u32 s1, s1, 0
	s_waitcnt vmcnt(3) lgkmcnt(0)
	s_barrier
	s_add_u32 s2, s2, 0x40000
	s_addc_u32 s3, s3, 0
	s_cmp_ge_i32 s76, s5
	s_mov_b32 s7, s4
	s_cbranch_scc0 .LBB0_276
	s_branch .LBB0_278
